# mLSTM prologue: the two per-wave gate scans run side by side (shuffle latencies overlap)
# speedup vs baseline: 1.0059x; 1.0059x over previous
; #define LAS __attribute__((address_space(3)))
; __device__ __forceinline__ void p2_mlstm(const Params& p, LAS unsigned char* lds) {
;     ...
;         for (int i = tid; i < (ML_G - ML_VT) / 4; i += 512) ((LAS unsigned*)(lds + ML_VT))[i] = 0u;
; #pragma unroll 1
;         for (int cc = 0; cc < 2; ++cc) {
;             const int ck = 2 * wid + cc; const int t0 = tokbase + ck * 128 + 2 * lane;
;             const float ig0 = GATES[(size_t)t0 * 8 + h], lf0 = GATES[(size_t)t0 * 8 + 4 + h], ig1 = GATES[(size_t)(t0 + 1) * 8 + h], lf1 = GATES[(size_t)(t0 + 1) * 8 + 4 + h];
;             float sc = lf0 + lf1;
; #pragma unroll
;             for (int off = 1; off < 64; off <<= 1) { const float t = __shfl_up(sc, off); if (lane >= off) sc += t; }
;             const float b1 = sc, b0 = sc - lf1;
;             const float u0 = ig0 - b0, u1 = ig1 - b1;
;             float cm = fmaxf(u0, u1);
; #pragma unroll
;             for (int off = 1; off < 64; off <<= 1) { const float t = __shfl_up(cm, off); if (lane >= off) cm = fmaxf(cm, t); }
;             float cprev = __shfl_up(cm, 1); if (lane == 0) cprev = -1e30f;
;             const int gi = ck * 128 + 2 * lane;
;             PU[gi] = u0; PU[gi + 1] = u1; PCM[gi] = fmaxf(cprev, u0); PCM[gi + 1] = cm; PB[gi] = b0; PB[gi + 1] = b1;
;             if (lane == 63) { PBT[ck] = b1; PCT[ck] = cm; }
;         }
.LBB0_238:
	v_add_u32_e32 v6, 0x200, v6
	s_movk_i32 s34, 0x35ff
	v_cmp_lt_u32_e32 vcc, s34, v6
	ds_write_b32 v5, v4
	s_or_b64 s[0:1], vcc, s[0:1]
	v_add_u32_e32 v5, 0x800, v5
	s_andn2_b64 exec, exec, s[0:1]
	s_cbranch_execnz .LBB0_238
	s_or_b64 exec, exec, s[0:1]
	s_lshl_b32 s0, s84, 2
	s_and_b32 s0, s0, 28
	s_ashr_i32 s83, s84, 6
	s_add_i32 s0, s0, s83
	s_lshl_b32 s0, s0, 9
	s_and_b32 s82, s83, 3
	s_and_b32 s0, s0, 0xfffff800
	s_lshl_b32 s1, s82, 2
	v_readlane_b32 s6, v254, 37
	s_add_u32 s34, s6, s1
	v_readlane_b32 s1, v254, 39
	v_or_b32_e32 v5, s0, v191
	s_addc_u32 s35, s1, 0
	s_mov_b32 s1, s36
	s_or_b32 s85, s36, 1
	s_lshl_b32 s80, s1, 7
	s_lshl_b32 s81, s85, 7
	v_add_u32_e32 v6, s80, v5
	v_add_u32_e32 v16, s81, v5
	v_ashrrev_i32_e32 v7, 31, v6
	v_ashrrev_i32_e32 v17, 31, v16
	s_waitcnt vmcnt(0)
	v_lshlrev_b64 v[8:9], 5, v[6:7]
	v_lshlrev_b64 v[18:19], 5, v[16:17]
	v_or_b32_e32 v6, 1, v6
	v_or_b32_e32 v16, 1, v16
	v_ashrrev_i32_e32 v7, 31, v6
	v_ashrrev_i32_e32 v17, 31, v16
	v_lshlrev_b64 v[6:7], 5, v[6:7]
	v_lshlrev_b64 v[16:17], 5, v[16:17]
	v_lshl_add_u64 v[8:9], s[34:35], 0, v[8:9]
	v_lshl_add_u64 v[18:19], s[34:35], 0, v[18:19]
	v_lshl_add_u64 v[6:7], s[34:35], 0, v[6:7]
	v_lshl_add_u64 v[16:17], s[34:35], 0, v[16:17]
	global_load_dword v10, v[8:9], off
	global_load_dword v20, v[18:19], off
	s_nop 0
	global_load_dword v8, v[8:9], off offset:16
	global_load_dword v18, v[18:19], off offset:16
	s_nop 0
	global_load_dword v11, v[6:7], off
	global_load_dword v21, v[16:17], off
	s_nop 0
	global_load_dword v7, v[6:7], off offset:16
	global_load_dword v17, v[16:17], off offset:16
	v_or_b32_e32 v14, s80, v191
	v_or_b32_e32 v24, s81, v191
	v_lshl_add_u32 v14, v14, 2, 0
	v_lshl_add_u32 v24, v24, 2, 0
	v_add_u32_e32 v15, 0x1e800, v14
	v_add_u32_e32 v25, 0x1e800, v24
	s_waitcnt vmcnt(0)
	v_add_f32_e32 v6, v8, v7
	v_add_f32_e32 v16, v18, v17
	ds_bpermute_b32 v8, v201, v6
	ds_bpermute_b32 v18, v201, v16
	s_waitcnt lgkmcnt(0)
	v_add_f32_e32 v8, v6, v8
	v_add_f32_e32 v18, v16, v18
	v_cndmask_b32_e64 v6, v8, v6, s[2:3]
	v_cndmask_b32_e64 v16, v18, v16, s[2:3]
	ds_bpermute_b32 v8, v208, v6
	ds_bpermute_b32 v18, v208, v16
	s_waitcnt lgkmcnt(0)
	v_add_f32_e32 v8, v6, v8
	v_add_f32_e32 v18, v16, v18
	v_cndmask_b32_e64 v6, v8, v6, s[16:17]
	v_cndmask_b32_e64 v16, v18, v16, s[16:17]
	ds_bpermute_b32 v8, v209, v6
	ds_bpermute_b32 v18, v209, v16
	s_waitcnt lgkmcnt(0)
	v_add_f32_e32 v8, v6, v8
	v_add_f32_e32 v18, v16, v18
	v_cndmask_b32_e64 v6, v8, v6, s[18:19]
	v_cndmask_b32_e64 v16, v18, v16, s[18:19]
	ds_bpermute_b32 v8, v210, v6
	ds_bpermute_b32 v18, v210, v16
	s_waitcnt lgkmcnt(0)
	v_add_f32_e32 v8, v6, v8
	v_add_f32_e32 v18, v16, v18
	v_cndmask_b32_e64 v6, v8, v6, s[20:21]
	v_cndmask_b32_e64 v16, v18, v16, s[20:21]
	ds_bpermute_b32 v8, v211, v6
	ds_bpermute_b32 v18, v211, v16
	s_waitcnt lgkmcnt(0)
	v_add_f32_e32 v8, v6, v8
	v_add_f32_e32 v18, v16, v18
	v_cndmask_b32_e64 v8, v8, v6, s[12:13]
	v_cndmask_b32_e64 v18, v18, v16, s[12:13]
	ds_bpermute_b32 v6, v213, v8
	ds_bpermute_b32 v16, v213, v18
	s_waitcnt lgkmcnt(0)
	v_add_f32_e32 v6, v8, v6
	v_add_f32_e32 v16, v18, v16
	v_cndmask_b32_e64 v9, v6, v8, s[22:23]
	v_cndmask_b32_e64 v19, v16, v18, s[22:23]
	v_sub_f32_e32 v8, v9, v7
	v_sub_f32_e32 v18, v19, v17
	v_sub_f32_e32 v10, v10, v8
	v_sub_f32_e32 v20, v20, v18
	v_sub_f32_e32 v11, v11, v9
	v_sub_f32_e32 v21, v21, v19
	v_max_f32_e32 v7, v10, v11
	v_max_f32_e32 v17, v20, v21
	ds_bpermute_b32 v12, v201, v7
	ds_bpermute_b32 v22, v201, v17
	ds_write_b64 v15, v[10:11]
	ds_write_b64 v25, v[20:21]
	s_waitcnt lgkmcnt(1)
	v_max_f32_e32 v12, v12, v12
	v_max_f32_e32 v22, v22, v22
	v_max_f32_e32 v12, v7, v12
	v_max_f32_e32 v22, v17, v22
	v_cndmask_b32_e64 v7, v12, v7, s[2:3]
	v_cndmask_b32_e64 v17, v22, v17, s[2:3]
	ds_bpermute_b32 v12, v208, v7
	ds_bpermute_b32 v22, v208, v17
	s_waitcnt lgkmcnt(0)
	v_max_f32_e32 v12, v12, v12
	v_max_f32_e32 v22, v22, v22
	v_max_f32_e32 v12, v7, v12
	v_max_f32_e32 v22, v17, v22
	v_cndmask_b32_e64 v7, v12, v7, s[16:17]
	v_cndmask_b32_e64 v17, v22, v17, s[16:17]
	ds_bpermute_b32 v12, v209, v7
	ds_bpermute_b32 v22, v209, v17
	s_waitcnt lgkmcnt(0)
	v_max_f32_e32 v12, v12, v12
	v_max_f32_e32 v22, v22, v22
	v_max_f32_e32 v12, v7, v12
	v_max_f32_e32 v22, v17, v22
	v_cndmask_b32_e64 v7, v12, v7, s[18:19]
	v_cndmask_b32_e64 v17, v22, v17, s[18:19]
	ds_bpermute_b32 v12, v210, v7
	ds_bpermute_b32 v22, v210, v17
	s_waitcnt lgkmcnt(0)
	v_max_f32_e32 v12, v12, v12
	v_max_f32_e32 v22, v22, v22
	v_max_f32_e32 v12, v7, v12
	v_max_f32_e32 v22, v17, v22
	v_cndmask_b32_e64 v7, v12, v7, s[20:21]
	v_cndmask_b32_e64 v17, v22, v17, s[20:21]
	ds_bpermute_b32 v12, v211, v7
	ds_bpermute_b32 v22, v211, v17
	s_waitcnt lgkmcnt(0)
	v_max_f32_e32 v12, v12, v12
	v_max_f32_e32 v22, v22, v22
	v_max_f32_e32 v12, v7, v12
	v_max_f32_e32 v22, v17, v22
	v_cndmask_b32_e64 v12, v12, v7, s[12:13]
	v_cndmask_b32_e64 v22, v22, v17, s[12:13]
	ds_bpermute_b32 v7, v213, v12
	ds_bpermute_b32 v17, v213, v22
	v_max_f32_e32 v13, v12, v12
	v_max_f32_e32 v23, v22, v22
	s_waitcnt lgkmcnt(0)
	v_max_f32_e32 v7, v7, v7
	v_max_f32_e32 v17, v17, v17
	v_max_f32_e32 v7, v13, v7
	v_max_f32_e32 v17, v23, v17
	v_cndmask_b32_e64 v13, v7, v12, s[22:23]
	v_cndmask_b32_e64 v23, v17, v22, s[22:23]
	ds_bpermute_b32 v12, v201, v13
	ds_bpermute_b32 v22, v201, v23
	s_waitcnt lgkmcnt(0)
	v_cndmask_b32_e64 v12, v12, v240, s[2:3]
	v_cndmask_b32_e64 v22, v22, v240, s[2:3]
	v_max_f32_e32 v11, v12, v12
	v_max_f32_e32 v21, v22, v22
	v_max_f32_e32 v12, v11, v10
	v_max_f32_e32 v22, v21, v20
	v_add_u32_e32 v10, 0x20800, v14
	v_add_u32_e32 v20, 0x20800, v24
	ds_write_b64 v10, v[12:13]
	ds_write_b64 v20, v[22:23]
	v_add_u32_e32 v10, 0x22800, v14
	v_add_u32_e32 v20, 0x22800, v24
	ds_write_b64 v10, v[8:9]
	ds_write_b64 v20, v[18:19]
	s_and_saveexec_b64 s[6:7], s[4:5]
	s_lshl_b32 s1, s1, 2
	s_lshl_b32 s85, s85, 2
	s_add_i32 s80, s1, 0x24800
	s_add_i32 s1, s1, 0x24840
	s_add_i32 s81, s85, 0x24800
	s_add_i32 s85, s85, 0x24840
	v_mov_b32_e32 v8, s80
	v_mov_b32_e32 v18, s81
	ds_write_b32 v8, v6
	ds_write_b32 v18, v16
	v_mov_b32_e32 v8, s1
	v_mov_b32_e32 v18, s85
	ds_write_b32 v8, v7
	ds_write_b32 v18, v17
	s_or_b64 exec, exec, s[6:7]
